# v65 with the dilated-phase start stagger shortened from 167 to 127 sleep units (the early-finishing workgroups now carry conversion work at their tail)
# baseline (speedup 1.0000x reference)
.LBB0_578:
	s_cmpk_eq_i32 s79, 0x100
	s_cselect_b64 s[4:5], -1, 0
	s_and_b64 s[8:9], s[4:5], exec
	s_mov_b64 s[0:1], s[70:71]
	s_cselect_b32 s3, s3, 0
	s_cselect_b32 s34, s2, 0x600
	s_add_i32 s35, s3, s82
	s_load_dwordx2 s[0:1], s[0:1], 0xb8
	s_movk_i32 s27, 0x600
	s_mov_b64 s[2:3], s[70:71]
	s_cmp_ge_i32 s35, s34
	s_waitcnt lgkmcnt(0)
	s_cbranch_scc1 .LBB0_614
	s_bitcmp1_b32 s82, 3
	s_cbranch_scc0 .Lp4_go
	s_sleep 127
	s_nop 0
